# MLA loop: next tile's global K/V prefetch issued after the first four K fragment reads (split), rest of the reads behind it
# baseline (speedup 1.0000x reference)
; #define MFMA(a, b, c) __builtin_amdgcn_mfma_f32_32x32x16_bf16((a), (b), (c), 0, 0, 0)
; DI float xhalf_max(float x) { const auto rr = __builtin_amdgcn_permlane32_swap(__float_as_uint(x), __float_as_uint(x), false, false); return fmaxf(__uint_as_float(rr[0]), __uint_as_float(rr[1])); }
; template <int DQK, int DV, bool BAND> ...
;     ...
;     if (PREF && kt + 1 < kt_hi) ALOAD(kt + 1);
;     if constexpr (DQK < 128) {
;       f32x16 p0, p1;
; #pragma unroll
;       for (int r = 0; r < 16; ++r) { p0[r] = 0.f; p1[r] = 0.f; }
;       __builtin_amdgcn_s_setprio(1);
; #pragma unroll
;       for (int d0 = 0; d0 < ND0; ++d0) {
;         const bf16x8 k0f = *(const bf16x8*)&Ks[r32 * KLD + d0 * 16 + hi * 8];
;         const bf16x8 k1f = *(const bf16x8*)&Ks[(32 + r32) * KLD + d0 * 16 + hi * 8];
;         p0 = MFMA(k0f, qf[d0], p0); p1 = MFMA(k1f, qf[d0], p1);
;       }
;       __builtin_amdgcn_s_setprio(0);
;       float mx = fmaxf(p0[0], p1[0]);
; #pragma unroll
;       for (int r = 1; r < 16; ++r) mx = fmaxf(mx, fmaxf(p0[r], p1[r]));
;       mx = xhalf_max(mx);
;       if (__builtin_amdgcn_ballot_w64(mx > m_run + 8.f) != 0ull) {
;         const float m_new = fmaxf(m_run, mx); const float m_use = (m_new == -INFINITY) ? 0.f : m_new;
;         const float alpha = __builtin_amdgcn_exp2f(m_run - m_use);
;         l_run *= alpha; m_run = m_new;
;         if (hi == 0) sc[r32] = alpha;
;         __builtin_amdgcn_fence(__ATOMIC_RELEASE, "wavefront");
;         __builtin_amdgcn_wave_barrier();
; #pragma unroll
;         for (int g4 = 0; g4 < 4; ++g4) { const f32x4 a4 = *(const f32x4*)&sc[8 * g4 + 4 * hi];
; #pragma unroll
;           for (int cb = 0; cb < NCB; ++cb)
; #pragma unroll
;             for (int j = 0; j < 4; ++j) o[cb][4 * g4 + j] *= a4[j]; }
;         __builtin_amdgcn_wave_barrier();
;       }
.LBB1_320:
	ds_read_b128 v[208:211], v132
	ds_read_b128 v[212:215], v132 offset:6656
	ds_read_b128 v[216:219], v132 offset:32
	ds_read_b128 v[220:223], v132 offset:6688
	s_cbranch_scc1 .Lmla_nold
	global_load_dwordx4 v[106:109], v118, s[14:15]
	global_load_dwordx4 v[98:101], v116, s[14:15]
	global_load_dwordx4 v[102:105], v114, s[14:15]
	global_load_dwordx4 v[90:93], v110, s[12:13]
	global_load_dwordx4 v[94:97], v112, s[12:13]
.Lmla_nold:
	ds_read_b128 v[224:227], v132 offset:64
	ds_read_b128 v[228:231], v132 offset:6720
	ds_read_b128 v[232:235], v132 offset:96
	ds_read_b128 v[236:239], v132 offset:6752
	ds_read_b128 v[240:243], v132 offset:128
	ds_read_b128 v[244:247], v132 offset:6784
	ds_read_b128 v[248:251], v132 offset:160
	ds_read_b128 v[134:137], v132 offset:6816
	s_waitcnt lgkmcnt(11)
	v_mfma_f32_32x32x16_bf16 v[34:49], v[208:211], v[66:69], v[150:165]
	s_waitcnt lgkmcnt(10)
	v_mfma_f32_32x32x16_bf16 v[50:65], v[212:215], v[66:69], v[150:165]
	s_waitcnt lgkmcnt(9)
	v_mfma_f32_32x32x16_bf16 v[34:49], v[216:219], v[70:73], v[34:49]
	s_waitcnt lgkmcnt(8)
	v_mfma_f32_32x32x16_bf16 v[50:65], v[220:223], v[70:73], v[50:65]
	s_waitcnt lgkmcnt(7)
	v_mfma_f32_32x32x16_bf16 v[34:49], v[224:227], v[74:77], v[34:49]
	s_waitcnt lgkmcnt(6)
	v_mfma_f32_32x32x16_bf16 v[50:65], v[228:231], v[74:77], v[50:65]
	s_waitcnt lgkmcnt(5)
	v_mfma_f32_32x32x16_bf16 v[34:49], v[232:235], v[78:81], v[34:49]
	s_waitcnt lgkmcnt(4)
	v_mfma_f32_32x32x16_bf16 v[50:65], v[236:239], v[78:81], v[50:65]
	s_waitcnt lgkmcnt(3)
	v_mfma_f32_32x32x16_bf16 v[34:49], v[240:243], v[82:85], v[34:49]
	s_waitcnt lgkmcnt(2)
	v_mfma_f32_32x32x16_bf16 v[50:65], v[244:247], v[82:85], v[50:65]
	s_waitcnt lgkmcnt(1)
	v_mfma_f32_32x32x16_bf16 v[34:49], v[248:251], v[86:89], v[34:49]
	s_waitcnt lgkmcnt(0)
	v_mfma_f32_32x32x16_bf16 v[50:65], v[134:137], v[86:89], v[50:65]
	ds_read2_b64 v[208:211], v166 offset0:128 offset1:130
	ds_read2_b64 v[212:215], v167 offset0:160 offset1:162
	ds_read2_b64 v[216:219], v166 offset0:136 offset1:138
	ds_read2_b64 v[220:223], v167 offset0:168 offset1:170
	ds_read2_b64 v[224:227], v166 offset0:132 offset1:134
	ds_read2_b64 v[228:231], v167 offset0:164 offset1:166
	ds_read2_b64 v[232:235], v166 offset0:140 offset1:142
	ds_read2_b64 v[236:239], v167 offset0:172 offset1:174
	s_nop 3
	v_max3_f32 v0, v34, v50, v35
	v_max3_f32 v134, v51, v36, v52
	v_max3_f32 v0, v0, v37, v53
	v_max3_f32 v134, v134, v38, v54
	v_max3_f32 v0, v0, v39, v55
	v_max3_f32 v134, v134, v40, v56
	v_max3_f32 v0, v0, v41, v57
	v_max3_f32 v134, v134, v42, v58
	v_max3_f32 v0, v0, v43, v59
	v_max3_f32 v134, v134, v44, v60
	v_max3_f32 v0, v0, v45, v61
	v_max3_f32 v134, v134, v46, v62
	v_max3_f32 v0, v0, v47, v63
	v_max3_f32 v134, v134, v48, v64
	v_max3_f32 v0, v0, v49, v65
	v_max_f32_e32 v0, v0, v134
	v_mov_b32_e32 v134, v0
	s_nop 1
	v_permlane32_swap_b32_e32 v0, v134
	v_max_f32_e32 v0, v0, v134
	v_sub_f32_e32 v0, v0, v150
	v_add_f32_e32 v134, 0x41000000, v133
	v_cmp_gt_f32_e32 vcc, v0, v134
	s_cbranch_vccz .LBB1_324
	v_max_f32_e32 v0, v0, v0
	v_max_f32_e32 v134, v133, v133
	v_max_f32_e32 v0, v134, v0
	v_cmp_neq_f32_e32 vcc, s7, v0
	s_nop 1
	v_cndmask_b32_e32 v134, 0, v0, vcc
	v_sub_f32_e32 v133, v133, v134
	v_exp_f32_e32 v133, v133
	v_add_f32_e32 v168, v150, v134
	s_and_saveexec_b64 s[22:23], s[36:37]
	ds_write_b32 v124, v133 offset:34816
	s_or_b64 exec, exec, s[22:23]
	s_waitcnt lgkmcnt(0)
	ds_read_b128 v[136:139], v120 offset:34816
	ds_read_b128 v[140:143], v120 offset:34848
	ds_read_b128 v[144:147], v120 offset:34880
	ds_read_b128 v[240:243], v120 offset:34912
	v_mul_f32_e32 v126, v126, v133
	v_sub_f32_e32 v34, v34, v168
	v_sub_f32_e32 v35, v35, v168
	v_sub_f32_e32 v36, v36, v168
	v_sub_f32_e32 v37, v37, v168
	v_sub_f32_e32 v38, v38, v168
	v_sub_f32_e32 v39, v39, v168
	v_sub_f32_e32 v40, v40, v168
	v_sub_f32_e32 v41, v41, v168
	v_sub_f32_e32 v42, v42, v168
	v_sub_f32_e32 v43, v43, v168
	v_sub_f32_e32 v44, v44, v168
	v_sub_f32_e32 v45, v45, v168
	v_sub_f32_e32 v46, v46, v168
	v_sub_f32_e32 v47, v47, v168
	v_sub_f32_e32 v48, v48, v168
	v_sub_f32_e32 v49, v49, v168
	v_sub_f32_e32 v50, v50, v168
	v_sub_f32_e32 v51, v51, v168
	v_sub_f32_e32 v52, v52, v168
	v_sub_f32_e32 v53, v53, v168
	v_sub_f32_e32 v54, v54, v168
	v_sub_f32_e32 v55, v55, v168
	v_sub_f32_e32 v56, v56, v168
	v_sub_f32_e32 v57, v57, v168
	v_sub_f32_e32 v58, v58, v168
	v_sub_f32_e32 v59, v59, v168
	v_sub_f32_e32 v60, v60, v168
	v_sub_f32_e32 v61, v61, v168
	v_sub_f32_e32 v62, v62, v168
	v_sub_f32_e32 v63, v63, v168
	v_sub_f32_e32 v64, v64, v168
	v_sub_f32_e32 v65, v65, v168
	v_sub_f32_e32 v150, 0, v134
	v_mov_b32_e32 v151, v150
	v_mov_b32_e32 v152, v150
	v_mov_b32_e32 v153, v150
	v_mov_b32_e32 v154, v150
	v_mov_b32_e32 v155, v150
	v_mov_b32_e32 v156, v150
	v_mov_b32_e32 v157, v150
	v_mov_b32_e32 v158, v150
	v_mov_b32_e32 v159, v150
	v_mov_b32_e32 v160, v150
	v_mov_b32_e32 v161, v150
	v_mov_b32_e32 v162, v150
	v_mov_b32_e32 v163, v150
	v_mov_b32_e32 v164, v150
	v_mov_b32_e32 v165, v150
	s_waitcnt lgkmcnt(0)
	v_pk_mul_f32 v[2:3], v[2:3], v[136:137]
	v_pk_mul_f32 v[4:5], v[4:5], v[138:139]
	v_pk_mul_f32 v[6:7], v[6:7], v[140:141]
	v_pk_mul_f32 v[8:9], v[8:9], v[142:143]
	v_pk_mul_f32 v[10:11], v[10:11], v[144:145]
	v_pk_mul_f32 v[12:13], v[12:13], v[146:147]
	v_pk_mul_f32 v[14:15], v[14:15], v[240:241]
	v_pk_mul_f32 v[16:17], v[16:17], v[242:243]
	v_pk_mul_f32 v[18:19], v[18:19], v[136:137]
	v_pk_mul_f32 v[20:21], v[20:21], v[138:139]
	v_pk_mul_f32 v[22:23], v[22:23], v[140:141]
	v_pk_mul_f32 v[24:25], v[24:25], v[142:143]
	v_pk_mul_f32 v[26:27], v[26:27], v[144:145]
	v_pk_mul_f32 v[28:29], v[28:29], v[146:147]
	v_pk_mul_f32 v[30:31], v[30:31], v[240:241]
	v_pk_mul_f32 v[32:33], v[32:33], v[242:243]
	s_branch .LBB1_325
